# next item's indexer query/head-weight tiles prefetched into dead gather-buffer registers during the attention tail (queue atomic at item start, id published via LDS), copied at the next prologue
# speedup vs baseline: 1.0218x; 1.0218x over previous
; __device__ __forceinline__ void attn_item(const Ptrs& P, unsigned char* lds, int b, int tq0, int tid) {
;     ...
; #pragma unroll
;         for (int q = 0; q < 4; ++q) { const bf16_t* qp = P.QI + (rowb + tq0 + q) * 1024 + r16 * 64 + 8 * g; Aq[q][0] = *(const bf16x8*)qp; Aq[q][1] = *(const bf16x8*)(qp + 32);
;             wq[q] = *(const f32x4*)(P.WI + (rowb + tq0 + q) * 16 + 4 * g); }
; __global__ void __launch_bounds__(512, 2) mega_fwd(Args args) {
;     ...
;             for (;;) {
;                 __syncthreads();
;                 if (tid == 0) *(volatile int*)(lds + 147712) = (int)atomicAdd(ctl + 64 * b, 1u);
;                 __syncthreads();
;                 const int item = *(volatile int*)(lds + 147712);
;                 if (item >= T / 4) break;
;                 attn_item(P, lds, b, 4 * ((T / 4 - 1) - item), tid);
.Lq_next:
	s_nop 0
	s_mov_b64 s[12:13], exec
	s_and_b64 exec, exec, s[0:1]
	v_mov_b32_e32 v0, 0x24104
	ds_write_b32 v0, v254
	s_mov_b64 exec, s[12:13]
	v_mov_b32_e32 v0, 0x24104
	s_waitcnt lgkmcnt(0)
	s_barrier
	ds_read_b32 v0, v0
	s_waitcnt lgkmcnt(0)
	s_branch .Lq_have_item
.Lpro_pf:
	s_and_b32 s14, s63, 0xffffffc0
	v_add_u32_e32 v164, s81, v124
	s_ashr_i32 s15, s14, 31
	v_lshl_add_u64 v[48:49], s[14:15], 0, v[182:183]
	v_lshlrev_b64 v[48:49], 7, v[48:49]
	v_lshl_add_u64 v[60:61], v[172:173], 0, v[48:49]
	v_lshrrev_b32_e32 v127, 3, v65
	v_sub_u32_e32 v128, 0x1ffd, v64
	v_sub_u32_e32 v129, 0x1ffe, v64
	v_mov_b64_e32 v[150:151], v[60:61]
	s_mov_b64 s[18:19], 0x1000
	v_lshl_add_u64 v[152:153], v[60:61], 0, s[18:19]
	global_load_dwordx4 v[48:51], v[150:151], off
	global_load_dwordx4 v[52:55], v[150:151], off offset:1024
	global_load_dwordx4 v[56:59], v[150:151], off offset:2048
	global_load_dwordx4 v[60:63], v[150:151], off offset:3072
	global_load_dwordx4 v[64:67], v[152:153], off
	global_load_dwordx4 v[68:71], v[152:153], off offset:1024
	global_load_dwordx4 v[72:75], v[152:153], off offset:2048
	global_load_dwordx4 v[76:79], v[152:153], off offset:3072
	s_mov_b64 s[18:19], 0x10000
	v_lshl_add_u64 v[150:151], v[150:151], 0, s[18:19]
	v_lshl_add_u64 v[152:153], v[152:153], 0, s[18:19]
	s_mov_b32 s20, 0
	v_lshl_add_u32 v130, s62, 8, v203
	v_add_u32_e32 v155, 0x10000, v130
	v_add_u32_e32 v154, s14, v179
	s_nop 0
	v_readfirstlane_b32 s14, v127
	s_waitcnt vmcnt(8)
	v_mov_b32_e32 v36, v20
	v_mov_b32_e32 v37, v21
	v_mov_b32_e32 v38, v22
	v_mov_b32_e32 v39, v23
	v_mov_b32_e32 v32, v24
	v_mov_b32_e32 v33, v25
	v_mov_b32_e32 v34, v26
	v_mov_b32_e32 v35, v27
	v_mov_b32_e32 v44, v156
	v_mov_b32_e32 v45, v157
	v_mov_b32_e32 v46, v158
	v_mov_b32_e32 v47, v159
	v_mov_b32_e32 v40, v160
	v_mov_b32_e32 v41, v161
	v_mov_b32_e32 v42, v162
	v_mov_b32_e32 v43, v163
	v_mov_b32_e32 v0, v88
	v_mov_b32_e32 v1, v89
	v_mov_b32_e32 v2, v90
	v_mov_b32_e32 v3, v91
	v_mov_b32_e32 v4, v92
	v_mov_b32_e32 v5, v93
	v_mov_b32_e32 v6, v94
	v_mov_b32_e32 v7, v95
	v_mov_b32_e32 v8, v116
	v_mov_b32_e32 v9, v117
	v_mov_b32_e32 v10, v118
	v_mov_b32_e32 v11, v119
	v_mov_b32_e32 v12, v120
	v_mov_b32_e32 v13, v121
	v_mov_b32_e32 v14, v122
	v_mov_b32_e32 v15, v123
	v_mov_b32_e32 v16, v248
	v_mov_b32_e32 v17, v249
	v_mov_b32_e32 v18, v250
	v_mov_b32_e32 v19, v251
	v_mov_b32_e32 v20, v132
	v_mov_b32_e32 v21, v133
	v_mov_b32_e32 v22, v134
	v_mov_b32_e32 v23, v135
	v_mov_b32_e32 v24, v140
	v_mov_b32_e32 v25, v141
	v_mov_b32_e32 v26, v142
	v_mov_b32_e32 v27, v143
	v_mov_b32_e32 v28, v144
	v_mov_b32_e32 v29, v145
	v_mov_b32_e32 v30, v146
	v_mov_b32_e32 v31, v147
	s_nop 3
	s_branch .Lidx_loop
	s_nop 0
	s_nop 0
	s_nop 0
	s_nop 0
	s_nop 0
	s_nop 0
	s_nop 0
	s_nop 0
	s_nop 0
	s_nop 0
	s_nop 0
	s_nop 0
	s_nop 0
	s_nop 0
	s_nop 0
	s_nop 0
	s_nop 0

; __global__ void __launch_bounds__(512, 2) mega_fwd(Args args) {
;     ...
;         for (int k = 0; k < NB; ++k) {
;             const int b = (hb + k) & 3;
;             for (;;) {
;                 __syncthreads();
;                 if (tid == 0) *(volatile int*)(lds + 147712) = (int)atomicAdd(ctl + 64 * b, 1u);
;                 __syncthreads();
;                 const int item = *(volatile int*)(lds + 147712);
.LBB0_466:
	s_barrier
	s_mov_b32 s96, 0
	s_nop 0
	s_nop 0
	s_nop 0
	s_nop 0
	s_nop 0
	s_nop 0
	s_nop 0
	s_nop 0
	s_nop 0
	s_nop 0
	s_nop 0
	s_nop 0
	s_nop 0
	s_nop 0
	s_nop 0
	s_and_saveexec_b64 s[12:13], s[0:1]
	s_cbranch_execz .LBB0_470
	s_mov_b64 s[16:17], exec
	v_mbcnt_lo_u32_b32 v0, s16, 0
	v_mbcnt_hi_u32_b32 v0, s17, v0
	v_cmp_eq_u32_e32 vcc, 0, v0
	s_and_saveexec_b64 s[14:15], vcc
	s_cbranch_execz .LBB0_469
	s_bcnt1_i32_b64 s16, s[16:17]
	v_mov_b32_e32 v1, s16
	global_atomic_add v1, v165, v1, s[46:47] sc0

; #define TILE_LOAD(SLOT, CC, TT) do { const bf16_t* kp = P.KI + (rowb + 64 * (CC) + 16 * (TT) + r16) * 64 + 8 * g; Bk[SLOT][0] = *(const bf16x8*)kp; Bk[SLOT][1] = *(const bf16x8*)(kp + 32); } while (0)
; #define TILE_MATH(SLOT, TT) do { _Pragma("unroll") for (int q = 0; q < 4; ++q) { f32x4 a = {0.f, 0.f, 0.f, 0.f}; \
;             a = mfma16(Aq[q][0], Bk[SLOT][0], a); a = mfma16(Aq[q][1], Bk[SLOT][1], a); \
;             pv[q][TT] = wq[q][0] * fmaxf(a[0], 0.f) + wq[q][1] * fmaxf(a[1], 0.f) + wq[q][2] * fmaxf(a[2], 0.f) + wq[q][3] * fmaxf(a[3], 0.f); } } while (0)
; __device__ __forceinline__ void attn_item(const Ptrs& P, unsigned char* lds, int b, int tq0, int tid) {
;     ...
;         for (int q = 0; q < 4; ++q) { const bf16_t* qp = P.QI + (rowb + tq0 + q) * 1024 + r16 * 64 + 8 * g; Aq[q][0] = *(const bf16x8*)qp; Aq[q][1] = *(const bf16x8*)(qp + 32);
;             wq[q] = *(const f32x4*)(P.WI + (rowb + tq0 + q) * 16 + 4 * g); }
;         unsigned* KB = (unsigned*)lds;
;         const int nch = (tmax >> 6) + 1;
;         const int ni = (w < nch) ? ((nch - w + 7) >> 3) : 0;
;         bf16x8 Bk[4][2];
;     ...
;         if (ni > 0) { TILE_LOAD(0, w, 0); TILE_LOAD(1, w, 1); }
; #pragma unroll 1
;         for (int it = 0; it < ni; ++it) {
;             const int c = 8 * it + w; const bool more = it + 1 < ni;
;             float pv[4][4], sv[4];
;             TILE_LOAD(2, c, 2); TILE_MATH(0, 0);
;             TILE_LOAD(3, c, 3); TILE_MATH(1, 1);
;             if (more) TILE_LOAD(0, c + 8, 0);
;             TILE_MATH(2, 2);
; __global__ void __launch_bounds__(512, 2) mega_fwd(Args args) {
;     ...
;                 if (tid == 0) *(volatile int*)(lds + 147712) = (int)atomicAdd(ctl + 64 * b, 1u);
.Lq_have_item:
	s_movk_i32 s12, 0x800
	s_waitcnt lgkmcnt(0)
	v_cmp_gt_i32_e32 vcc, s12, v0
	s_mov_b64 s[12:13], -1
	s_and_saveexec_b64 s[70:71], vcc
	s_cbranch_execz .LBB0_465
	s_and_saveexec_b64 s[90:91], s[0:1]
	v_mov_b32_e32 v255, 1
	global_atomic_add v254, v165, v255, s[46:47] sc0
	s_mov_b64 exec, s[90:91]
	s_nop 0
	s_nop 0
	s_nop 0
	s_nop 0
	s_nop 0
	s_nop 0
	s_nop 0
	s_nop 0
	s_nop 0
	s_nop 0
	s_nop 0
	v_lshlrev_b32_e32 v64, 2, v0
	v_sub_u32_e32 v124, 0x1ffc, v64
	v_readfirstlane_b32 s63, v188
	s_movk_i32 s12, 0xfc
	s_lshr_b32 s62, s63, 6
	v_cmp_lt_u32_e32 vcc, s12, v124
	s_and_saveexec_b64 s[12:13], vcc
	s_xor_b64 s[60:61], exec, s[12:13]
	s_cbranch_execz .LBB0_913
	v_sub_u32_e32 v126, 0x1fff, v64
	v_lshrrev_b32_e32 v125, 6, v126
	v_subrev_u32_e32 v0, s62, v125
	v_add_u32_e32 v65, 8, v0
	v_cmp_le_u32_e32 vcc, s62, v125
	v_cmp_lt_u32_e64 s[12:13], 7, v65
	s_and_b64 s[14:15], vcc, s[12:13]
	s_and_saveexec_b64 s[12:13], s[14:15]
	s_cbranch_execz .LBB0_479
	s_cmp_eq_u32 s96, 1
	s_cbranch_scc1 .Lpro_pf
	s_nop 0
	s_nop 0
	s_nop 0
	s_nop 0
	s_nop 0
	s_nop 0
	s_nop 0
	s_nop 0
	s_nop 0
	s_nop 0
	s_nop 0
	s_nop 0
	s_nop 0
	s_nop 0
	s_and_b32 s14, s63, 0xffffffc0
	v_add_u32_e32 v164, s81, v124
	s_ashr_i32 s15, s14, 31
	v_or_b32_e32 v40, 1, v164
	v_mov_b32_e32 v41, v165
	v_or_b32_e32 v32, 2, v164
	v_mov_b32_e32 v33, v165
	v_or_b32_e32 v34, 3, v164
	v_mov_b32_e32 v35, v165
	v_lshl_add_u64 v[48:49], s[14:15], 0, v[182:183]
	v_lshlrev_b64 v[0:1], 11, v[164:165]
	v_lshlrev_b64 v[8:9], 11, v[40:41]
	v_lshlrev_b64 v[16:17], 11, v[32:33]
	v_lshlrev_b64 v[24:25], 11, v[34:35]
	v_lshlrev_b64 v[34:35], 6, v[34:35]
	v_lshlrev_b64 v[32:33], 6, v[32:33]
	v_lshlrev_b64 v[40:41], 6, v[40:41]
	v_lshlrev_b64 v[42:43], 6, v[164:165]
	v_lshlrev_b64 v[48:49], 7, v[48:49]
	v_lshl_add_u64 v[4:5], v[168:169], 0, v[0:1]
	v_lshl_add_u64 v[12:13], v[168:169], 0, v[8:9]
	v_lshl_add_u64 v[20:21], v[168:169], 0, v[16:17]
	v_lshl_add_u64 v[28:29], v[168:169], 0, v[24:25]
	v_lshl_add_u64 v[34:35], v[170:171], 0, v[34:35]
	v_lshl_add_u64 v[36:37], v[170:171], 0, v[32:33]
	v_lshl_add_u64 v[40:41], v[170:171], 0, v[40:41]
	v_lshl_add_u64 v[44:45], v[170:171], 0, v[42:43]
	v_lshl_add_u64 v[60:61], v[172:173], 0, v[48:49]
	global_load_dwordx4 v[0:3], v[4:5], off
	s_nop 0
	global_load_dwordx4 v[4:7], v[4:5], off offset:64
	s_nop 0
	global_load_dwordx4 v[8:11], v[12:13], off
	s_nop 0
	global_load_dwordx4 v[12:15], v[12:13], off offset:64
	s_nop 0
	global_load_dwordx4 v[16:19], v[20:21], off
	s_nop 0
	global_load_dwordx4 v[20:23], v[20:21], off offset:64
	s_nop 0
	global_load_dwordx4 v[24:27], v[28:29], off
	s_nop 0
	global_load_dwordx4 v[28:31], v[28:29], off offset:64
	s_nop 0
	global_load_dwordx4 v[32:35], v[34:35], off
	s_nop 0
	global_load_dwordx4 v[36:39], v[36:37], off
	s_nop 0
	global_load_dwordx4 v[40:43], v[40:41], off
	s_nop 0
	global_load_dwordx4 v[44:47], v[44:45], off
	s_nop 0
	v_lshrrev_b32_e32 v127, 3, v65
	v_sub_u32_e32 v128, 0x1ffd, v64
	v_sub_u32_e32 v129, 0x1ffe, v64
	v_mov_b64_e32 v[150:151], v[60:61]
	s_mov_b64 s[18:19], 0x1000
	v_lshl_add_u64 v[152:153], v[60:61], 0, s[18:19]
	global_load_dwordx4 v[48:51], v[150:151], off
	global_load_dwordx4 v[52:55], v[150:151], off offset:1024
	global_load_dwordx4 v[56:59], v[150:151], off offset:2048
	global_load_dwordx4 v[60:63], v[150:151], off offset:3072
	global_load_dwordx4 v[64:67], v[152:153], off
	global_load_dwordx4 v[68:71], v[152:153], off offset:1024
	global_load_dwordx4 v[72:75], v[152:153], off offset:2048
	global_load_dwordx4 v[76:79], v[152:153], off offset:3072
	s_mov_b64 s[18:19], 0x10000
	v_lshl_add_u64 v[150:151], v[150:151], 0, s[18:19]
	v_lshl_add_u64 v[152:153], v[152:153], 0, s[18:19]
	s_mov_b32 s20, 0
	v_lshl_add_u32 v130, s62, 8, v203
	v_add_u32_e32 v155, 0x10000, v130
	v_add_u32_e32 v154, s14, v179
	s_nop 0
	v_readfirstlane_b32 s14, v127
.Lidx_loop:
	s_waitcnt vmcnt(6)
	v_mfma_f32_16x16x32_bf16 v[80:83], v[0:3], v[48:51], 0
	v_mfma_f32_16x16x32_bf16 v[84:87], v[8:11], v[48:51], 0
	v_mfma_f32_16x16x32_bf16 v[88:91], v[16:19], v[48:51], 0
	v_mfma_f32_16x16x32_bf16 v[92:95], v[24:27], v[48:51], 0
	v_mfma_f32_16x16x32_bf16 v[80:83], v[4:7], v[52:55], v[80:83]
	v_mfma_f32_16x16x32_bf16 v[84:87], v[12:15], v[52:55], v[84:87]
	v_mfma_f32_16x16x32_bf16 v[88:91], v[20:23], v[52:55], v[88:91]
	v_mfma_f32_16x16x32_bf16 v[92:95], v[28:31], v[52:55], v[92:95]
	global_load_dwordx4 v[48:51], v[150:151], off
	global_load_dwordx4 v[52:55], v[150:151], off offset:1024
	s_waitcnt vmcnt(6)
	v_mfma_f32_16x16x32_bf16 v[96:99], v[0:3], v[56:59], 0
	v_mfma_f32_16x16x32_bf16 v[100:103], v[8:11], v[56:59], 0
	v_mfma_f32_16x16x32_bf16 v[104:107], v[16:19], v[56:59], 0
	v_mfma_f32_16x16x32_bf16 v[108:111], v[24:27], v[56:59], 0
	v_mfma_f32_16x16x32_bf16 v[96:99], v[4:7], v[60:63], v[96:99]
	v_mfma_f32_16x16x32_bf16 v[100:103], v[12:15], v[60:63], v[100:103]
	v_mfma_f32_16x16x32_bf16 v[104:107], v[20:23], v[60:63], v[104:107]
	v_mfma_f32_16x16x32_bf16 v[108:111], v[28:31], v[60:63], v[108:111]
	global_load_dwordx4 v[56:59], v[150:151], off offset:2048
	global_load_dwordx4 v[60:63], v[150:151], off offset:3072
	v_max_f32_e32 v80, 0, v80
	v_max_f32_e32 v84, 0, v84
	v_max_f32_e32 v88, 0, v88
	v_max_f32_e32 v92, 0, v92
	v_max_f32_e32 v81, 0, v81
	v_max_f32_e32 v85, 0, v85
	v_max_f32_e32 v89, 0, v89
	v_max_f32_e32 v93, 0, v93
	v_max_f32_e32 v82, 0, v82
	v_max_f32_e32 v86, 0, v86
	v_max_f32_e32 v90, 0, v90
	v_max_f32_e32 v94, 0, v94
	v_max_f32_e32 v83, 0, v83
	v_max_f32_e32 v87, 0, v87
	v_max_f32_e32 v91, 0, v91
	v_max_f32_e32 v95, 0, v95
	v_mul_f32_e32 v132, v44, v80
	v_mul_f32_e32 v136, v40, v84
	v_mul_f32_e32 v140, v36, v88
	v_mul_f32_e32 v144, v32, v92
	v_fmac_f32_e32 v132, v45, v81
	v_fmac_f32_e32 v136, v41, v85
	v_fmac_f32_e32 v140, v37, v89
	v_fmac_f32_e32 v144, v33, v93
	v_fmac_f32_e32 v132, v46, v82
	v_fmac_f32_e32 v136, v42, v86
	v_fmac_f32_e32 v140, v38, v90
	v_fmac_f32_e32 v144, v34, v94
	v_fmac_f32_e32 v132, v47, v83
	v_fmac_f32_e32 v136, v43, v87
	v_fmac_f32_e32 v140, v39, v91
	v_fmac_f32_e32 v144, v35, v95
	s_waitcnt vmcnt(6)
; __device__ __forceinline__ unsigned f2key(float f) { const unsigned u = __builtin_bit_cast(unsigned, f); return (u & 0x80000000u) ? ~u : (u | 0x80000000u); }
; #define TILE_LOAD(SLOT, CC, TT) do { const bf16_t* kp = P.KI + (rowb + 64 * (CC) + 16 * (TT) + r16) * 64 + 8 * g; Bk[SLOT][0] = *(const bf16x8*)kp; Bk[SLOT][1] = *(const bf16x8*)(kp + 32); } while (0)
; #define TILE_MATH(SLOT, TT) do { _Pragma("unroll") for (int q = 0; q < 4; ++q) { f32x4 a = {0.f, 0.f, 0.f, 0.f}; \
;             a = mfma16(Aq[q][0], Bk[SLOT][0], a); a = mfma16(Aq[q][1], Bk[SLOT][1], a); \
;             pv[q][TT] = wq[q][0] * fmaxf(a[0], 0.f) + wq[q][1] * fmaxf(a[1], 0.f) + wq[q][2] * fmaxf(a[2], 0.f) + wq[q][3] * fmaxf(a[3], 0.f); } } while (0)
; __device__ __forceinline__ void attn_item(const Ptrs& P, unsigned char* lds, int b, int tq0, int tid) {
;     ...
;             TILE_LOAD(2, c, 2); TILE_MATH(0, 0);
;             TILE_LOAD(3, c, 3); TILE_MATH(1, 1);
;             if (more) TILE_LOAD(0, c + 8, 0);
;             TILE_MATH(2, 2);
;             if (more) TILE_LOAD(1, c + 8, 1);
;             TILE_MATH(3, 3);
; #pragma unroll
;             for (int q = 0; q < 4; ++q) { float a0 = pv[q][0], b0 = pv[q][2], a1 = pv[q][1], b1 = pv[q][3];
;                 asm("s_nop 1\n\tv_permlane32_swap_b32 %0, %1" : "+v"(a0), "+v"(b0));
;                 asm("s_nop 1\n\tv_permlane32_swap_b32 %0, %1" : "+v"(a1), "+v"(b1));
;                 float x = a0 + b0, y = a1 + b1;
;                 asm("s_nop 1\n\tv_permlane16_swap_b32 %0, %1" : "+v"(x), "+v"(y));
;                 sv[q] = x + y; }
;             const int s = 64 * c + lane;
; #pragma unroll
;             for (int q = 0; q < 4; ++q) KB[q * 8192 + s] = (s <= tq0 + q) ? f2key(sv[q]) : 0u;
	v_mfma_f32_16x16x32_bf16 v[80:83], v[0:3], v[64:67], 0
	v_mfma_f32_16x16x32_bf16 v[84:87], v[8:11], v[64:67], 0
	v_mfma_f32_16x16x32_bf16 v[88:91], v[16:19], v[64:67], 0
	v_mfma_f32_16x16x32_bf16 v[92:95], v[24:27], v[64:67], 0
	v_mfma_f32_16x16x32_bf16 v[80:83], v[4:7], v[68:71], v[80:83]
	v_mfma_f32_16x16x32_bf16 v[84:87], v[12:15], v[68:71], v[84:87]
	v_mfma_f32_16x16x32_bf16 v[88:91], v[20:23], v[68:71], v[88:91]
	v_mfma_f32_16x16x32_bf16 v[92:95], v[28:31], v[68:71], v[92:95]
	global_load_dwordx4 v[64:67], v[152:153], off
	global_load_dwordx4 v[68:71], v[152:153], off offset:1024
	v_max_f32_e32 v96, 0, v96
	v_max_f32_e32 v100, 0, v100
	v_max_f32_e32 v104, 0, v104
	v_max_f32_e32 v108, 0, v108
	v_max_f32_e32 v97, 0, v97
	v_max_f32_e32 v101, 0, v101
	v_max_f32_e32 v105, 0, v105
	v_max_f32_e32 v109, 0, v109
	v_max_f32_e32 v98, 0, v98
	v_max_f32_e32 v102, 0, v102
	v_max_f32_e32 v106, 0, v106
	v_max_f32_e32 v110, 0, v110
	v_max_f32_e32 v99, 0, v99
	v_max_f32_e32 v103, 0, v103
	v_max_f32_e32 v107, 0, v107
	v_max_f32_e32 v111, 0, v111
	v_mul_f32_e32 v133, v44, v96
	v_mul_f32_e32 v137, v40, v100
	v_mul_f32_e32 v141, v36, v104
	v_mul_f32_e32 v145, v32, v108
	v_fmac_f32_e32 v133, v45, v97
	v_fmac_f32_e32 v137, v41, v101
	v_fmac_f32_e32 v141, v37, v105
	v_fmac_f32_e32 v145, v33, v109
	v_fmac_f32_e32 v133, v46, v98
	v_fmac_f32_e32 v137, v42, v102
	v_fmac_f32_e32 v141, v38, v106
	v_fmac_f32_e32 v145, v34, v110
	v_fmac_f32_e32 v133, v47, v99
	v_fmac_f32_e32 v137, v43, v103
	v_fmac_f32_e32 v141, v39, v107
	v_fmac_f32_e32 v145, v35, v111
	s_waitcnt vmcnt(6)
	v_mfma_f32_16x16x32_bf16 v[96:99], v[0:3], v[72:75], 0
	v_mfma_f32_16x16x32_bf16 v[100:103], v[8:11], v[72:75], 0
	v_mfma_f32_16x16x32_bf16 v[104:107], v[16:19], v[72:75], 0
	v_mfma_f32_16x16x32_bf16 v[108:111], v[24:27], v[72:75], 0
	v_mfma_f32_16x16x32_bf16 v[96:99], v[4:7], v[76:79], v[96:99]
	v_mfma_f32_16x16x32_bf16 v[100:103], v[12:15], v[76:79], v[100:103]
	v_mfma_f32_16x16x32_bf16 v[104:107], v[20:23], v[76:79], v[104:107]
	v_mfma_f32_16x16x32_bf16 v[108:111], v[28:31], v[76:79], v[108:111]
	global_load_dwordx4 v[72:75], v[152:153], off offset:2048
	global_load_dwordx4 v[76:79], v[152:153], off offset:3072
	v_lshl_add_u64 v[150:151], v[150:151], 0, s[18:19]
	v_lshl_add_u64 v[152:153], v[152:153], 0, s[18:19]
	v_max_f32_e32 v80, 0, v80
	v_max_f32_e32 v84, 0, v84
	v_max_f32_e32 v88, 0, v88
	v_max_f32_e32 v92, 0, v92
	v_max_f32_e32 v81, 0, v81
	v_max_f32_e32 v85, 0, v85
	v_max_f32_e32 v89, 0, v89
	v_max_f32_e32 v93, 0, v93
	v_max_f32_e32 v82, 0, v82
	v_max_f32_e32 v86, 0, v86
	v_max_f32_e32 v90, 0, v90
	v_max_f32_e32 v94, 0, v94
	v_max_f32_e32 v83, 0, v83
	v_max_f32_e32 v87, 0, v87
	v_max_f32_e32 v91, 0, v91
	v_max_f32_e32 v95, 0, v95
	v_mul_f32_e32 v134, v44, v80
	v_mul_f32_e32 v138, v40, v84
	v_mul_f32_e32 v142, v36, v88
	v_mul_f32_e32 v146, v32, v92
	v_fmac_f32_e32 v134, v45, v81
	v_fmac_f32_e32 v138, v41, v85
	v_fmac_f32_e32 v142, v37, v89
	v_fmac_f32_e32 v146, v33, v93
	v_fmac_f32_e32 v134, v46, v82
	v_fmac_f32_e32 v138, v42, v86
	v_fmac_f32_e32 v142, v38, v90
	v_fmac_f32_e32 v146, v34, v94
	v_fmac_f32_e32 v134, v47, v83
	v_fmac_f32_e32 v138, v43, v87
	v_fmac_f32_e32 v142, v39, v91
	v_fmac_f32_e32 v146, v35, v95
	v_max_f32_e32 v96, 0, v96
	v_max_f32_e32 v100, 0, v100
	v_max_f32_e32 v104, 0, v104
	v_max_f32_e32 v108, 0, v108
	v_max_f32_e32 v97, 0, v97
	v_max_f32_e32 v101, 0, v101
	v_max_f32_e32 v105, 0, v105
	v_max_f32_e32 v109, 0, v109
	v_max_f32_e32 v98, 0, v98
	v_max_f32_e32 v102, 0, v102
	v_max_f32_e32 v106, 0, v106
	v_max_f32_e32 v110, 0, v110
	v_max_f32_e32 v99, 0, v99
	v_max_f32_e32 v103, 0, v103
	v_max_f32_e32 v107, 0, v107
	v_max_f32_e32 v111, 0, v111
	v_mul_f32_e32 v135, v44, v96
	v_mul_f32_e32 v139, v40, v100
	v_mul_f32_e32 v143, v36, v104
	v_mul_f32_e32 v147, v32, v108
	v_fmac_f32_e32 v135, v45, v97
	v_fmac_f32_e32 v139, v41, v101
	v_fmac_f32_e32 v143, v37, v105
	v_fmac_f32_e32 v147, v33, v109
	v_fmac_f32_e32 v135, v46, v98
	v_fmac_f32_e32 v139, v42, v102
	v_fmac_f32_e32 v143, v38, v106
	v_fmac_f32_e32 v147, v34, v110
	v_fmac_f32_e32 v135, v47, v99
	v_fmac_f32_e32 v139, v43, v103
	v_fmac_f32_e32 v143, v39, v107
	v_fmac_f32_e32 v147, v35, v111
	s_nop 1
	v_permlane32_swap_b32_e32 v132, v134
	v_permlane32_swap_b32_e32 v133, v135
	v_permlane32_swap_b32_e32 v136, v138
	v_permlane32_swap_b32_e32 v137, v139
	v_permlane32_swap_b32_e32 v140, v142
	v_permlane32_swap_b32_e32 v141, v143
	v_permlane32_swap_b32_e32 v144, v146
	v_permlane32_swap_b32_e32 v145, v147
	v_add_f32_e32 v112, v132, v134
	v_add_f32_e32 v113, v133, v135
	v_add_f32_e32 v114, v136, v138
	v_add_f32_e32 v115, v137, v139
	v_add_f32_e32 v116, v140, v142
	v_add_f32_e32 v117, v141, v143
	v_add_f32_e32 v118, v144, v146
	v_add_f32_e32 v119, v145, v147
	s_nop 1
	v_permlane16_swap_b32_e32 v112, v113
	v_permlane16_swap_b32_e32 v114, v115
	v_permlane16_swap_b32_e32 v116, v117
	v_permlane16_swap_b32_e32 v118, v119
	v_add_u32_e32 v156, 0x800, v130
	v_add_u32_e32 v157, 0x800, v155
	v_add_f32_e32 v120, v112, v113
	v_add_f32_e32 v121, v114, v115
	v_add_f32_e32 v122, v116, v117
	v_add_f32_e32 v123, v118, v119
	v_ashrrev_i32_e32 v112, 31, v120
	v_ashrrev_i32_e32 v113, 31, v121
	v_ashrrev_i32_e32 v114, 31, v122
	v_ashrrev_i32_e32 v115, 31, v123
	v_cmp_le_u32_e32 vcc, v154, v124
	v_cmp_le_u32_e64 s[16:17], v154, v128
	v_cmp_le_u32_e64 s[44:45], v154, v129
	v_cmp_le_u32_e64 s[78:79], v154, v126
	v_or_b32_e32 v112, 0x80000000, v112
	v_or_b32_e32 v113, 0x80000000, v113
	v_or_b32_e32 v114, 0x80000000, v114
	v_or_b32_e32 v115, 0x80000000, v115
	v_xor_b32_e32 v120, v120, v112
	v_xor_b32_e32 v121, v121, v113
	v_xor_b32_e32 v122, v122, v114
	v_xor_b32_e32 v123, v123, v115
	v_cndmask_b32_e32 v120, 0, v120, vcc
	v_cndmask_b32_e64 v121, 0, v121, s[16:17]
	v_cndmask_b32_e64 v122, 0, v122, s[44:45]
	v_cndmask_b32_e64 v123, 0, v123, s[78:79]
	ds_write2st64_b32 v130, v120, v121 offset1:128
	ds_write2st64_b32 v155, v122, v123 offset1:128
	v_mov_b32_e32 v130, v156
	v_mov_b32_e32 v155, v157
	v_add_u32_e32 v154, 0x200, v154
	s_add_i32 s20, s20, 1
	s_cmp_lt_u32 s20, s14
	s_cbranch_scc1 .Lidx_loop
	s_waitcnt vmcnt(0)
	s_cmp_lg_u32 s62, 0
	s_cbranch_scc1 .Lpf_nb
	v_mov_b32_e32 v112, 0x24108
	s_mov_b64 s[94:95], exec
	s_mov_b64 exec, s[0:1]
	ds_write_b32 v112, v254
	s_mov_b64 exec, s[94:95]
	s_waitcnt lgkmcnt(0)
.Lpf_nb:
	s_branch .LBB0_479
	s_nop 0
	s_nop 0
	s_nop 0
	s_nop 0
	s_nop 0
	s_nop 0
	s_nop 0
	s_nop 0
	s_nop 0
	s_nop 0
	s_nop 0
	s_nop 0
	s_nop 0

; __device__ __forceinline__ void attn_item(const Ptrs& P, unsigned char* lds, int b, int tq0, int tid) {
;     ...
;     if (tmax < 256 || (DBG & 4)) {
;         for (int i = tid; i < 1024; i += 512) sel[i] = (unsigned short)(((i & 255) <= tq0 + (i >> 8)) ? (i & 255) : 0);
;         __syncthreads();
.LBB0_913:
	s_or_saveexec_b64 s[14:15], s[60:61]
	v_mov_b32_e32 v32, s65
	v_mov_b32_e32 v219, s64
	s_xor_b64 exec, exec, s[14:15]
	s_cbranch_execz .LBB0_921
	s_and_saveexec_b64 s[90:91], s[0:1]
	v_mov_b32_e32 v0, 0x24108
	v_mov_b32_e32 v1, 0xffff
	ds_write_b32 v0, v1
	s_mov_b64 exec, s[90:91]
	s_nop 0
	s_nop 0
	s_nop 0
	s_nop 0
	s_nop 0
	s_nop 0
	s_nop 0
	s_nop 0
	s_nop 0
	s_nop 0
	s_nop 0
	s_nop 0
	s_nop 0
	v_sub_u32_e32 v0, v208, v64
	v_sub_u32_e32 v1, v210, v64
	s_mov_b32 s18, 0
	s_mov_b64 s[16:17], 0
	v_mov_b32_e32 v2, v209
	s_branch .LBB0_916

; __device__ __forceinline__ void attn_item(const Ptrs& P, unsigned char* lds, int b, int tq0, int tid) {
;     ...
;     {
;         float* cmb = (float*)stw;
; #pragma unroll
;         for (int dt = 0; dt < 8; ++dt)
; #pragma unroll
;             for (int j = 0; j < 4; ++j) cmb[(dt * 4 + j) * 64 + lane] = half ? oacc[dt][j] : oacc[8 + dt][j];
; #pragma unroll
;         for (int j = 0; j < 4; ++j) { cmb[2048 + j * 64 + lane] = mrun[j]; cmb[2304 + j * 64 + lane] = lrun[j]; }
;         asm volatile("s_waitcnt lgkmcnt(0)" ::: "memory");
;         if (lane == 0) xa[48 + w] = aseq;
;         while (xa[48 + (w ^ 1)] != aseq) { }
.LBB0_928:
	v_mov_b32_e32 v18, 0x24108
	ds_read_b32 v18, v18
	s_mov_b32 s96, 0
	s_waitcnt lgkmcnt(0)
	v_readfirstlane_b32 s90, v18
	s_nop 3
	s_cmp_gt_u32 s90, 0x7ff
	s_cbranch_scc1 .Lpf_skip
	s_lshl_b32 s90, s90, 2
	s_sub_u32 s90, 0x1ffc, s90
	s_cmp_lt_u32 s90, 0xfd
	s_cbranch_scc1 .Lpf_skip
	s_add_u32 s90, s90, s81
	s_mov_b32 s95, 0
	s_lshl_b32 s94, s90, 11
	v_lshl_add_u64 v[18:19], v[168:169], 0, s[94:95]
	s_add_u32 s94, s94, 0x1000
	v_lshl_add_u64 v[28:29], v[168:169], 0, s[94:95]
	s_lshl_b32 s94, s90, 6
	v_lshl_add_u64 v[30:31], v[170:171], 0, s[94:95]
	global_load_dwordx4 v[88:91], v[18:19], off
	global_load_dwordx4 v[92:95], v[18:19], off offset:64
	global_load_dwordx4 v[116:119], v[18:19], off offset:2048
	global_load_dwordx4 v[120:123], v[18:19], off offset:2112
	global_load_dwordx4 v[248:251], v[28:29], off
	global_load_dwordx4 v[132:135], v[28:29], off offset:64
	global_load_dwordx4 v[140:143], v[28:29], off offset:2048
	global_load_dwordx4 v[144:147], v[28:29], off offset:2112
	global_load_dwordx4 v[156:159], v[30:31], off
	global_load_dwordx4 v[160:163], v[30:31], off offset:64
	global_load_dwordx4 v[20:23], v[30:31], off offset:128
	global_load_dwordx4 v[24:27], v[30:31], off offset:192
	s_mov_b32 s96, 1
.Lpf_skip:
	s_nop 0
	s_nop 0
	s_nop 0
	s_nop 0
	s_nop 0
	s_nop 0
	s_nop 0
	s_nop 0
	s_nop 0
	s_nop 0
	v_lshl_add_u32 v0, v179, 2, s12
	v_cmp_eq_u32_e64 s[12:13], 0, v219
	s_nop 1
	v_cndmask_b32_e64 v3, v109, v149, s[12:13]
	v_cndmask_b32_e64 v4, v108, v148, s[12:13]
	v_cndmask_b32_e64 v1, v111, v151, s[12:13]
	v_cndmask_b32_e64 v2, v110, v150, s[12:13]
	ds_write2st64_b32 v0, v4, v3 offset1:1
	ds_write2st64_b32 v0, v2, v1 offset0:2 offset1:3
	v_cndmask_b32_e64 v3, v101, v137, s[12:13]
	v_cndmask_b32_e64 v4, v100, v136, s[12:13]
	v_cndmask_b32_e64 v1, v103, v139, s[12:13]
	v_cndmask_b32_e64 v2, v102, v138, s[12:13]
	ds_write2st64_b32 v0, v4, v3 offset0:4 offset1:5
	ds_write2st64_b32 v0, v2, v1 offset0:6 offset1:7
	v_cndmask_b32_e64 v3, v85, v125, s[12:13]
	v_cndmask_b32_e64 v4, v84, v124, s[12:13]
	v_cndmask_b32_e64 v1, v87, v127, s[12:13]
	v_cndmask_b32_e64 v2, v86, v126, s[12:13]
	ds_write2st64_b32 v0, v4, v3 offset0:8 offset1:9
	ds_write2st64_b32 v0, v2, v1 offset0:10 offset1:11
	v_cndmask_b32_e64 v3, v69, v113, s[12:13]
	v_cndmask_b32_e64 v4, v68, v112, s[12:13]
	v_cndmask_b32_e64 v1, v71, v115, s[12:13]
	v_cndmask_b32_e64 v2, v70, v114, s[12:13]
	ds_write2st64_b32 v0, v4, v3 offset0:12 offset1:13
	ds_write2st64_b32 v0, v2, v1 offset0:14 offset1:15
	v_cndmask_b32_e64 v3, v49, v105, s[12:13]
	v_cndmask_b32_e64 v4, v48, v104, s[12:13]
	v_cndmask_b32_e64 v1, v51, v107, s[12:13]
	v_cndmask_b32_e64 v2, v50, v106, s[12:13]
	ds_write2st64_b32 v0, v4, v3 offset0:16 offset1:17
	ds_write2st64_b32 v0, v2, v1 offset0:18 offset1:19
	v_cndmask_b32_e64 v3, v41, v97, s[12:13]
	v_cndmask_b32_e64 v4, v40, v96, s[12:13]
	v_cndmask_b32_e64 v1, v43, v99, s[12:13]
	v_cndmask_b32_e64 v2, v42, v98, s[12:13]
	ds_write2st64_b32 v0, v4, v3 offset0:20 offset1:21
	ds_write2st64_b32 v0, v2, v1 offset0:22 offset1:23
	v_cndmask_b32_e64 v3, v37, v81, s[12:13]
	v_cndmask_b32_e64 v4, v36, v80, s[12:13]
	v_cndmask_b32_e64 v1, v39, v83, s[12:13]
	v_cndmask_b32_e64 v2, v38, v82, s[12:13]
	ds_write2st64_b32 v0, v4, v3 offset0:24 offset1:25
	ds_write2st64_b32 v0, v2, v1 offset0:26 offset1:27
	v_cndmask_b32_e64 v3, v33, v45, s[12:13]
	v_cndmask_b32_e64 v4, v32, v44, s[12:13]
	v_cndmask_b32_e64 v1, v35, v47, s[12:13]
	v_cndmask_b32_e64 v2, v34, v46, s[12:13]
	ds_write2st64_b32 v0, v4, v3 offset0:28 offset1:29
	ds_write2st64_b32 v0, v2, v1 offset0:30 offset1:31
	ds_write2st64_b32 v0, v164, v233 offset0:32 offset1:33
	ds_write2st64_b32 v0, v191, v190 offset0:36 offset1:37
	ds_write2st64_b32 v0, v234, v235 offset0:34 offset1:35
	ds_write2st64_b32 v0, v187, v186 offset0:38 offset1:39
	s_waitcnt lgkmcnt(0)
	s_and_saveexec_b64 s[14:15], s[4:5]
	s_cbranch_execz .LBB0_930
	s_addk_i32 s16, 0xc0
	v_mov_b32_e32 v0, s16
	v_mov_b32_e32 v1, s21
	ds_write_b32 v0, v218
	s_waitcnt lgkmcnt(0)

; __device__ __forceinline__ unsigned cvt_pk_bf16(float lo, float hi) { unsigned r; asm volatile("v_cvt_pk_bf16_f32 %0, %1, %2" : "=v"(r) : "v"(lo), "v"(hi)); return r; }
; __device__ __forceinline__ void attn_item(const Ptrs& P, unsigned char* lds, int b, int tq0, int tid) {
;     ...
;         if (lane == 0) xa[48 + w] = aseq;
;         while (xa[48 + (w ^ 1)] != aseq) { }
;         const float* pc = (const float*)(stg + (w ^ 1) * 32 * SP);
;         float wa[4], wb[4];
; #pragma unroll
;         for (int j = 0; j < 4; ++j) { const float mo = pc[2048 + j * 64 + lane], lo = pc[2304 + j * 64 + lane];
;             const float mm = fmaxf(mrun[j], mo); const float ea = __expf(mrun[j] - mm), eb = __expf(mo - mm);
;             const float inv = 1.f / (lrun[j] * ea + lo * eb); wa[j] = ea * inv; wb[j] = eb * inv; }
;         bf16_t* op = P.QL + (rowb + tq) * 4096;
; #pragma unroll
;         for (int dt = 0; dt < 8; ++dt)
; #pragma unroll
;             for (int j = 0; j < 4; ++j) { const float v = (half ? oacc[8 + dt][j] : oacc[dt][j]) * wa[j] + pc[(dt * 4 + j) * 64 + lane] * wb[j];
;                 op[(4 * g + j) * 256 + 16 * (8 * half + dt) + r16] = (bf16_t)(cvt_pk_bf16(v, 0.f) & 0xffffu); }
.LBB0_931:
	v_mov_b64_e32 v[0:1], s[20:21]
	ds_read_b32 v0, v0
	s_waitcnt lgkmcnt(0)
	v_cmp_eq_u32_e32 vcc, v0, v218
	s_or_b64 s[14:15], vcc, s[14:15]
	s_andn2_b64 exec, exec, s[14:15]
	s_cbranch_execnz .LBB0_931
	s_or_b64 exec, exec, s[14:15]
	s_mulk_i32 s16, 0x4200
	v_add_u32_e32 v8, s16, v203
	ds_read2st64_b32 v[0:1], v8 offset1:32
	v_max_f32_e32 v4, v164, v164
	ds_read2st64_b32 v[2:3], v8 offset0:35 offset1:36
	v_cndmask_b32_e64 v17, v149, v109, s[12:13]
	s_waitcnt lgkmcnt(1)
	v_max_f32_e32 v5, v1, v1
	v_max_f32_e32 v4, v4, v5
	v_sub_f32_e32 v1, v1, v4
	v_sub_f32_e32 v5, v164, v4
	v_mul_f32_e32 v1, 0x3fb8aa3b, v1
	v_mul_f32_e32 v4, 0x3fb8aa3b, v5
	v_exp_f32_e32 v1, v1
	v_exp_f32_e32 v9, v4
	ds_read2st64_b32 v[4:5], v8 offset0:37 offset1:38
	ds_read_b32 v10, v8 offset:9984
	ds_read2st64_b32 v[6:7], v8 offset0:33 offset1:34
	s_waitcnt lgkmcnt(3)
	v_mul_f32_e32 v3, v3, v1
	v_fmac_f32_e32 v3, v191, v9
	v_div_scale_f32 v11, s[14:15], v3, v3, 1.0
	v_rcp_f32_e32 v12, v11
	s_nop 0
	v_fma_f32 v13, -v11, v12, 1.0
	v_fmac_f32_e32 v12, v13, v12
	v_div_scale_f32 v13, vcc, 1.0, v3, 1.0
	v_mul_f32_e32 v14, v13, v12
	v_fma_f32 v15, -v11, v14, v13
	v_fmac_f32_e32 v14, v15, v12
	v_fma_f32 v11, -v11, v14, v13
	s_waitcnt lgkmcnt(0)
	v_max_f32_e32 v13, v6, v6
	v_max_f32_e32 v15, v233, v233
	v_max_f32_e32 v13, v15, v13
	v_sub_f32_e32 v6, v6, v13
	v_sub_f32_e32 v15, v233, v13
	v_mul_f32_e32 v6, 0x3fb8aa3b, v6
	v_mul_f32_e32 v15, 0x3fb8aa3b, v15
	v_exp_f32_e32 v6, v6
	v_exp_f32_e32 v13, v15
	v_div_fmas_f32 v11, v11, v12, v14
	v_div_fixup_f32 v3, v11, v3, 1.0
	v_mul_f32_e32 v4, v4, v6
	v_fmac_f32_e32 v4, v190, v13
	v_div_scale_f32 v12, s[14:15], v4, v4, 1.0
	v_rcp_f32_e32 v14, v12
	v_mul_f32_e32 v9, v9, v3
	v_mul_f32_e32 v3, v1, v3
	v_mul_f32_e32 v0, v0, v3
	v_fma_f32 v1, -v12, v14, 1.0
	v_fmac_f32_e32 v14, v1, v14
	v_div_scale_f32 v1, vcc, 1.0, v4, 1.0
	v_mul_f32_e32 v11, v1, v14
	v_fma_f32 v15, -v12, v11, v1
	v_fmac_f32_e32 v11, v15, v14
	v_fma_f32 v1, -v12, v11, v1
	v_max_f32_e32 v12, v7, v7
	v_max_f32_e32 v15, v234, v234
	v_max_f32_e32 v12, v15, v12
	v_sub_f32_e32 v7, v7, v12
	v_sub_f32_e32 v15, v234, v12
	v_mul_f32_e32 v7, 0x3fb8aa3b, v7
	v_mul_f32_e32 v15, 0x3fb8aa3b, v15
	v_exp_f32_e32 v7, v7
	v_exp_f32_e32 v12, v15
	v_div_fmas_f32 v1, v1, v14, v11
	v_div_fixup_f32 v1, v1, v4, 1.0
	v_mul_f32_e32 v5, v5, v7
	v_fmac_f32_e32 v5, v187, v12
	v_div_scale_f32 v11, s[14:15], v5, v5, 1.0
	v_rcp_f32_e32 v14, v11
	v_mul_f32_e32 v4, v13, v1
	v_mul_f32_e32 v6, v6, v1
	v_fma_f32 v1, -v11, v14, 1.0
	v_fmac_f32_e32 v14, v1, v14
	v_div_scale_f32 v1, vcc, 1.0, v5, 1.0
	v_mul_f32_e32 v13, v1, v14
	v_fma_f32 v15, -v11, v13, v1
	v_fmac_f32_e32 v13, v15, v14
	v_fma_f32 v1, -v11, v13, v1
	v_max_f32_e32 v11, v2, v2
	v_max_f32_e32 v15, v235, v235
	v_max_f32_e32 v11, v15, v11
	v_sub_f32_e32 v2, v2, v11
	v_sub_f32_e32 v15, v235, v11
	v_mul_f32_e32 v2, 0x3fb8aa3b, v2
	v_mul_f32_e32 v15, 0x3fb8aa3b, v15
	v_exp_f32_e32 v2, v2
	v_exp_f32_e32 v11, v15
	v_div_fmas_f32 v1, v1, v14, v13
	v_div_fixup_f32 v1, v1, v5, 1.0
	v_mul_f32_e32 v10, v10, v2
	v_fmac_f32_e32 v10, v186, v11
	v_div_scale_f32 v13, s[14:15], v10, v10, 1.0
	v_rcp_f32_e32 v14, v13
	v_mul_f32_e32 v5, v12, v1
	v_mul_f32_e32 v7, v7, v1
	v_fma_f32 v1, -v13, v14, 1.0
	v_fmac_f32_e32 v14, v1, v14
	v_div_scale_f32 v1, vcc, 1.0, v10, 1.0
	v_mul_f32_e32 v12, v1, v14
	v_fma_f32 v15, -v13, v12, v1
	v_fmac_f32_e32 v12, v15, v14
	v_cndmask_b32_e64 v15, v148, v108, s[12:13]
	v_fmac_f32_e32 v0, v15, v9
	v_cvt_pk_bf16_f32 v15, v0, v165
	ds_read_b32 v16, v8 offset:256
	v_fma_f32 v13, -v13, v12, v1
	v_or_b32_e32 v1, v181, v204
	v_lshlrev_b32_e32 v164, 1, v1
	v_lshl_add_u64 v[0:1], v[184:185], 0, v[164:165]
	global_store_short v[0:1], v15, off
	s_waitcnt lgkmcnt(0)
	v_mul_f32_e32 v15, v6, v16
	v_fmac_f32_e32 v15, v17, v4
	v_cvt_pk_bf16_f32 v15, v15, v165
	ds_read_b32 v16, v8 offset:512
	v_div_fmas_f32 v12, v13, v14, v12
	v_div_fixup_f32 v10, v12, v10, 1.0
	v_cndmask_b32_e64 v12, v150, v110, s[12:13]
	global_store_short v[0:1], v15, off offset:512
	s_waitcnt lgkmcnt(0)
	v_mul_f32_e32 v13, v7, v16
	v_fmac_f32_e32 v13, v12, v5
	v_cvt_pk_bf16_f32 v12, v13, v165
	ds_read_b32 v13, v8 offset:768
	v_mul_f32_e32 v2, v2, v10
	v_mul_f32_e32 v11, v11, v10
	v_cndmask_b32_e64 v10, v151, v111, s[12:13]
	global_store_short v[0:1], v12, off offset:1024
	s_waitcnt lgkmcnt(0)
	v_mul_f32_e32 v12, v2, v13
	v_fmac_f32_e32 v12, v10, v11
	v_cvt_pk_bf16_f32 v10, v12, v165
	ds_read_b32 v12, v8 offset:1024
	global_store_short v[0:1], v10, off offset:1536
	v_cndmask_b32_e64 v10, v136, v100, s[12:13]
	v_cndmask_b32_e64 v13, v137, v101, s[12:13]
	s_waitcnt lgkmcnt(0)
	v_mul_f32_e32 v12, v3, v12
	v_fmac_f32_e32 v12, v10, v9
	v_cvt_pk_bf16_f32 v10, v12, v165
	ds_read_b32 v12, v8 offset:1280
	global_store_short v[0:1], v10, off offset:32
	s_waitcnt lgkmcnt(0)
	v_mul_f32_e32 v10, v6, v12
	v_fmac_f32_e32 v10, v13, v4
	v_cvt_pk_bf16_f32 v10, v10, v165
	ds_read_b32 v12, v8 offset:1536
	v_cndmask_b32_e64 v13, v138, v102, s[12:13]
	global_store_short v[0:1], v10, off offset:544
	s_waitcnt lgkmcnt(0)
	v_mul_f32_e32 v10, v7, v12
	v_fmac_f32_e32 v10, v13, v5
	v_cvt_pk_bf16_f32 v10, v10, v165
	ds_read_b32 v12, v8 offset:1792
	v_cndmask_b32_e64 v13, v139, v103, s[12:13]
	global_store_short v[0:1], v10, off offset:1056
	s_waitcnt lgkmcnt(0)
	v_mul_f32_e32 v10, v2, v12
	v_fmac_f32_e32 v10, v13, v11
	v_cvt_pk_bf16_f32 v10, v10, v165
	ds_read_b32 v12, v8 offset:2048
	global_store_short v[0:1], v10, off offset:1568
	v_cndmask_b32_e64 v10, v124, v84, s[12:13]
	v_cndmask_b32_e64 v13, v125, v85, s[12:13]
	s_waitcnt lgkmcnt(0)
; __device__ __forceinline__ unsigned cvt_pk_bf16(float lo, float hi) { unsigned r; asm volatile("v_cvt_pk_bf16_f32 %0, %1, %2" : "=v"(r) : "v"(lo), "v"(hi)); return r; }
; __device__ __forceinline__ void attn_item(const Ptrs& P, unsigned char* lds, int b, int tq0, int tid) {
;     ...
;         bf16_t* op = P.QL + (rowb + tq) * 4096;
; #pragma unroll
;         for (int dt = 0; dt < 8; ++dt)
; #pragma unroll
;             for (int j = 0; j < 4; ++j) { const float v = (half ? oacc[8 + dt][j] : oacc[dt][j]) * wa[j] + pc[(dt * 4 + j) * 64 + lane] * wb[j];
;                 op[(4 * g + j) * 256 + 16 * (8 * half + dt) + r16] = (bf16_t)(cvt_pk_bf16(v, 0.f) & 0xffffu); }
	v_mul_f32_e32 v12, v3, v12
	v_fmac_f32_e32 v12, v10, v9
	v_cvt_pk_bf16_f32 v10, v12, v165
	ds_read_b32 v12, v8 offset:2304
	global_store_short v[0:1], v10, off offset:64
	s_waitcnt lgkmcnt(0)
	v_mul_f32_e32 v10, v6, v12
	v_fmac_f32_e32 v10, v13, v4
	v_cvt_pk_bf16_f32 v10, v10, v165
	ds_read_b32 v12, v8 offset:2560
	v_cndmask_b32_e64 v13, v126, v86, s[12:13]
	global_store_short v[0:1], v10, off offset:576
	s_waitcnt lgkmcnt(0)
	v_mul_f32_e32 v10, v7, v12
	v_fmac_f32_e32 v10, v13, v5
	v_cvt_pk_bf16_f32 v10, v10, v165
	ds_read_b32 v12, v8 offset:2816
	v_cndmask_b32_e64 v13, v127, v87, s[12:13]
	global_store_short v[0:1], v10, off offset:1088
	s_waitcnt lgkmcnt(0)
	v_mul_f32_e32 v10, v2, v12
	v_fmac_f32_e32 v10, v13, v11
	v_cvt_pk_bf16_f32 v10, v10, v165
	ds_read_b32 v12, v8 offset:3072
	global_store_short v[0:1], v10, off offset:1600
	v_cndmask_b32_e64 v10, v112, v68, s[12:13]
	v_cndmask_b32_e64 v13, v113, v69, s[12:13]
	s_waitcnt lgkmcnt(0)
	v_mul_f32_e32 v12, v3, v12
	v_fmac_f32_e32 v12, v10, v9
	v_cvt_pk_bf16_f32 v10, v12, v165
	ds_read_b32 v12, v8 offset:3328
	global_store_short v[0:1], v10, off offset:96
	s_waitcnt lgkmcnt(0)
	v_mul_f32_e32 v10, v6, v12
	v_fmac_f32_e32 v10, v13, v4
	v_cvt_pk_bf16_f32 v10, v10, v165
	ds_read_b32 v12, v8 offset:3584
	v_cndmask_b32_e64 v13, v114, v70, s[12:13]
	global_store_short v[0:1], v10, off offset:608
	s_waitcnt lgkmcnt(0)
	v_mul_f32_e32 v10, v7, v12
	v_fmac_f32_e32 v10, v13, v5
	v_cvt_pk_bf16_f32 v10, v10, v165
	ds_read_b32 v12, v8 offset:3840
	v_cndmask_b32_e64 v13, v115, v71, s[12:13]
	global_store_short v[0:1], v10, off offset:1120
	s_waitcnt lgkmcnt(0)
	v_mul_f32_e32 v10, v2, v12
	v_fmac_f32_e32 v10, v13, v11
	v_cvt_pk_bf16_f32 v10, v10, v165
	ds_read_b32 v12, v8 offset:4096
	global_store_short v[0:1], v10, off offset:1632
	v_cndmask_b32_e64 v10, v104, v48, s[12:13]
	v_cndmask_b32_e64 v13, v105, v49, s[12:13]
	s_waitcnt lgkmcnt(0)
	v_mul_f32_e32 v12, v3, v12
	v_fmac_f32_e32 v12, v10, v9
	v_cvt_pk_bf16_f32 v10, v12, v165
	ds_read_b32 v12, v8 offset:4352
	global_store_short v[0:1], v10, off offset:128
	s_waitcnt lgkmcnt(0)
	v_mul_f32_e32 v10, v6, v12
	v_fmac_f32_e32 v10, v13, v4
	v_cvt_pk_bf16_f32 v10, v10, v165
	ds_read_b32 v12, v8 offset:4608
	v_cndmask_b32_e64 v13, v106, v50, s[12:13]
	global_store_short v[0:1], v10, off offset:640
	s_waitcnt lgkmcnt(0)
	v_mul_f32_e32 v10, v7, v12
	v_fmac_f32_e32 v10, v13, v5
	v_cvt_pk_bf16_f32 v10, v10, v165
	ds_read_b32 v12, v8 offset:4864
	v_cndmask_b32_e64 v13, v107, v51, s[12:13]
	global_store_short v[0:1], v10, off offset:1152
	s_waitcnt lgkmcnt(0)
	v_mul_f32_e32 v10, v2, v12
	v_fmac_f32_e32 v10, v13, v11
	v_cvt_pk_bf16_f32 v10, v10, v165
	ds_read_b32 v12, v8 offset:5120
	global_store_short v[0:1], v10, off offset:1664
	v_cndmask_b32_e64 v10, v96, v40, s[12:13]
	v_cndmask_b32_e64 v13, v97, v41, s[12:13]
	s_waitcnt lgkmcnt(0)
	v_mul_f32_e32 v12, v3, v12
	v_fmac_f32_e32 v12, v10, v9
	v_cvt_pk_bf16_f32 v10, v12, v165
	ds_read_b32 v12, v8 offset:5376
	global_store_short v[0:1], v10, off offset:160
	s_waitcnt lgkmcnt(0)
	v_mul_f32_e32 v10, v6, v12
	v_fmac_f32_e32 v10, v13, v4
	v_cvt_pk_bf16_f32 v10, v10, v165
	ds_read_b32 v12, v8 offset:5632
	v_cndmask_b32_e64 v13, v98, v42, s[12:13]
	global_store_short v[0:1], v10, off offset:672
	s_waitcnt lgkmcnt(0)
	v_mul_f32_e32 v10, v7, v12
	v_fmac_f32_e32 v10, v13, v5
	v_cvt_pk_bf16_f32 v10, v10, v165
	ds_read_b32 v12, v8 offset:5888
	v_cndmask_b32_e64 v13, v99, v43, s[12:13]
	global_store_short v[0:1], v10, off offset:1184
	s_waitcnt lgkmcnt(0)
	v_mul_f32_e32 v10, v2, v12
	v_fmac_f32_e32 v10, v13, v11
	v_cvt_pk_bf16_f32 v10, v10, v165
	ds_read_b32 v12, v8 offset:6144
	global_store_short v[0:1], v10, off offset:1696
	v_cndmask_b32_e64 v10, v80, v36, s[12:13]
	v_cndmask_b32_e64 v13, v81, v37, s[12:13]
	s_waitcnt lgkmcnt(0)
	v_mul_f32_e32 v12, v3, v12
	v_fmac_f32_e32 v12, v10, v9
	v_cvt_pk_bf16_f32 v10, v12, v165
	ds_read_b32 v12, v8 offset:6400
	global_store_short v[0:1], v10, off offset:192
	s_waitcnt lgkmcnt(0)
	v_mul_f32_e32 v10, v6, v12
	v_fmac_f32_e32 v10, v13, v4
	v_cvt_pk_bf16_f32 v10, v10, v165
	ds_read_b32 v12, v8 offset:6656
	v_cndmask_b32_e64 v13, v82, v38, s[12:13]
	global_store_short v[0:1], v10, off offset:704
	s_waitcnt lgkmcnt(0)
	v_mul_f32_e32 v10, v7, v12
	v_fmac_f32_e32 v10, v13, v5
	v_cvt_pk_bf16_f32 v10, v10, v165
	ds_read_b32 v12, v8 offset:6912
	v_cndmask_b32_e64 v13, v83, v39, s[12:13]
	global_store_short v[0:1], v10, off offset:1216
	s_waitcnt lgkmcnt(0)
	v_mul_f32_e32 v10, v2, v12
	v_fmac_f32_e32 v10, v13, v11
	v_cvt_pk_bf16_f32 v10, v10, v165
	ds_read_b32 v12, v8 offset:7168
	global_store_short v[0:1], v10, off offset:1728
	v_cndmask_b32_e64 v10, v44, v32, s[12:13]
	s_waitcnt lgkmcnt(0)
	v_mul_f32_e32 v3, v3, v12
	v_fmac_f32_e32 v3, v10, v9
	v_cvt_pk_bf16_f32 v3, v3, v165
	ds_read_b32 v9, v8 offset:7424
	v_cndmask_b32_e64 v10, v45, v33, s[12:13]
	global_store_short v[0:1], v3, off offset:224
	s_waitcnt lgkmcnt(0)
	v_mul_f32_e32 v3, v6, v9
	v_fmac_f32_e32 v3, v10, v4
	v_cvt_pk_bf16_f32 v3, v3, v165
	ds_read_b32 v4, v8 offset:7680
	v_cndmask_b32_e64 v6, v46, v34, s[12:13]
	global_store_short v[0:1], v3, off offset:736
	s_waitcnt lgkmcnt(0)
	v_mul_f32_e32 v3, v7, v4
	v_fmac_f32_e32 v3, v6, v5
	v_cvt_pk_bf16_f32 v3, v3, v165
	ds_read_b32 v4, v8 offset:7936
	v_cndmask_b32_e64 v5, v47, v35, s[12:13]
	s_xor_b64 s[12:13], exec, -1
	global_store_short v[0:1], v3, off offset:1248
	s_waitcnt lgkmcnt(0)
	v_mul_f32_e32 v2, v2, v4
	v_fmac_f32_e32 v2, v5, v11
	v_cvt_pk_bf16_f32 v2, v2, v165
	global_store_short v[0:1], v2, off offset:1760
	s_branch .Lq_next
